# P9 cross-attention scores: Q fragment loads issued in the staging section before the next chunk's K prefetch (compute waits no longer pull the K prefetch in front of the first MFMA); K prefetch uncond
# speedup vs baseline: 1.0012x; 1.0012x over previous
; #define LAS __attribute__((address_space(3)))
; __device__ __forceinline__ void xa_item(int it, LAS unsigned char* lds, const bf16_t* XQ, const bf16_t* XK, bf16_t* PB, int tid, int wid, int lane) {
;     ...
;         __syncthreads();
; #pragma unroll
;         for (int i = 0; i < 8; ++i) *(LAS u32x4*)(KL + ((tid >> 4) + 32 * i) * KS + 8 * (tid & 15)) = R[i];
;         if (c < 3) {
; #pragma unroll
;             for (int i = 0; i < 8; ++i) R[i] = *(const u32x4*)(ksrc + (size_t)(32 * i) * 2048 + (c + 1) * 128);
;         }
;         __syncthreads();
;         if (wid < 4) {
; #pragma unroll 2
;             for (int ks = 0; ks < 8; ++ks) {
;                 const bf16x8 qv = *(const bf16x8*)(qp + c * 128 + 16 * ks);
.LBB0_1513:
	s_cmp_eq_u32 s26, 3
	s_waitcnt vmcnt(0)
	s_barrier
	ds_write_b128 v196, v[146:149]
	ds_write_b128 v196, v[150:153] offset:8704
	ds_write_b128 v196, v[154:157] offset:17408
	ds_write_b128 v196, v[158:161] offset:26112
	ds_write_b128 v196, v[162:165] offset:34816
	ds_write_b128 v196, v[166:169] offset:43520
	ds_write_b128 v196, v[170:173] offset:52224
	ds_write_b128 v196, v[174:177] offset:60928
	s_andn2_b64 vcc, exec, s[8:9]
	s_cbranch_vccnz .Lp9_noq
	global_load_dwordx4 v[6:9], v[188:189], off offset:-32
	global_load_dwordx4 v[238:241], v[188:189], off offset:96
	global_load_dwordx4 v[10:13], v[188:189], off
	global_load_dwordx4 v[230:233], v[188:189], off offset:32
	global_load_dwordx4 v[234:237], v[188:189], off offset:64
	global_load_dwordx4 v[242:245], v[188:189], off offset:128
	global_load_dwordx4 v[246:249], v[188:189], off offset:160
	global_load_dwordx4 v[250:253], v[188:189], off offset:192
.Lp9_noq:
	s_lshl_b32 s6, s26, 8
	v_lshl_add_u64 v[198:199], v[186:187], 0, s[6:7]
	v_add_co_u32_e32 v200, vcc, 0x20000, v198
	s_nop 1
	v_addc_co_u32_e32 v201, vcc, 0, v199, vcc
	global_load_dwordx4 v[146:149], v[198:199], off offset:256
	global_load_dwordx4 v[150:153], v[200:201], off offset:256
	v_add_co_u32_e32 v200, vcc, 0x40000, v198
	s_nop 1
	v_addc_co_u32_e32 v201, vcc, 0, v199, vcc
	v_add_co_u32_e32 v202, vcc, 0x60000, v198
	s_nop 1
	v_addc_co_u32_e32 v203, vcc, 0, v199, vcc
	global_load_dwordx4 v[154:157], v[200:201], off offset:256
	global_load_dwordx4 v[158:161], v[202:203], off offset:256
	v_add_co_u32_e32 v200, vcc, 0x80000, v198
	s_nop 1
	v_addc_co_u32_e32 v201, vcc, 0, v199, vcc
	v_add_co_u32_e32 v202, vcc, 0xa0000, v198
	s_nop 1
	v_addc_co_u32_e32 v203, vcc, 0, v199, vcc
	global_load_dwordx4 v[162:165], v[200:201], off offset:256
	global_load_dwordx4 v[166:169], v[202:203], off offset:256
	v_add_co_u32_e32 v200, vcc, 0xc0000, v198
	s_nop 1
	v_addc_co_u32_e32 v201, vcc, 0, v199, vcc
	v_add_co_u32_e32 v198, vcc, 0xe0000, v198
	s_nop 1
	v_addc_co_u32_e32 v199, vcc, 0, v199, vcc
	global_load_dwordx4 v[170:173], v[200:201], off offset:256
	global_load_dwordx4 v[174:177], v[198:199], off offset:256

; #define LAS __attribute__((address_space(3)))
; #define MFMA32(a, b, c) __builtin_amdgcn_mfma_f32_32x32x16_bf16((a), (b), (c), 0, 0, 0)
; __device__ __forceinline__ void xa_item(int it, LAS unsigned char* lds, const bf16_t* XQ, const bf16_t* XK, bf16_t* PB, int tid, int wid, int lane) {
;     ...
;         if (wid < 4) {
; #pragma unroll 2
;             for (int ks = 0; ks < 8; ++ks) {
;                 const bf16x8 qv = *(const bf16x8*)(qp + c * 128 + 16 * ks);
; #pragma unroll
;                 for (int mt = 0; mt < 8; ++mt) st[mt] = MFMA32(*(const LAS bf16x8*)(KL + (32 * mt + x) * KS + 16 * ks + 8 * hi), qv, st[mt]);
;             }
.LBB0_1517:
	s_mov_b32 s6, 0
	v_add_u32_e32 v3, s6, v195
	ds_read_b128 v[14:17], v3
	ds_read_b128 v[198:201], v3 offset:32
	v_add_u32_e32 v185, s6, v194
	v_add_u32_e32 v210, s6, v193
	v_add_u32_e32 v218, s6, v192
	v_add_u32_e32 v226, s6, v191
	s_waitcnt vmcnt(15) lgkmcnt(1)
	v_mfma_f32_32x32x16_bf16 v[130:145], v[14:17], v[6:9], v[130:145]
	ds_read_b128 v[14:17], v185
	ds_read_b128 v[202:205], v185 offset:32
	s_waitcnt lgkmcnt(1)
	v_mfma_f32_32x32x16_bf16 v[114:129], v[14:17], v[6:9], v[114:129]
	ds_read_b128 v[14:17], v3 offset:17408
	ds_read_b128 v[206:209], v3 offset:17440
	s_waitcnt lgkmcnt(1)
	v_mfma_f32_32x32x16_bf16 v[98:113], v[14:17], v[6:9], v[98:113]
	ds_read_b128 v[14:17], v210
	ds_read_b128 v[210:213], v210 offset:32
	s_waitcnt lgkmcnt(1)
	v_mfma_f32_32x32x16_bf16 v[82:97], v[14:17], v[6:9], v[82:97]
	ds_read_b128 v[14:17], v3 offset:34816
	ds_read_b128 v[214:217], v3 offset:34848
	s_waitcnt lgkmcnt(1)
	v_mfma_f32_32x32x16_bf16 v[66:81], v[14:17], v[6:9], v[66:81]
	ds_read_b128 v[14:17], v218
	ds_read_b128 v[218:221], v218 offset:32
	s_waitcnt lgkmcnt(1)
	v_mfma_f32_32x32x16_bf16 v[50:65], v[14:17], v[6:9], v[50:65]
	ds_read_b128 v[14:17], v3 offset:52224
	ds_read_b128 v[222:225], v3 offset:52256
	s_waitcnt lgkmcnt(1)
	v_mfma_f32_32x32x16_bf16 v[34:49], v[14:17], v[6:9], v[34:49]
	ds_read_b128 v[14:17], v226
	ds_read_b128 v[226:229], v226 offset:32
	s_waitcnt lgkmcnt(1)
	v_mfma_f32_32x32x16_bf16 v[18:33], v[14:17], v[6:9], v[18:33]
	s_waitcnt vmcnt(13)
	v_mfma_f32_32x32x16_bf16 v[130:145], v[198:201], v[10:13], v[130:145]
	v_mfma_f32_32x32x16_bf16 v[114:129], v[202:205], v[10:13], v[114:129]
	v_mfma_f32_32x32x16_bf16 v[98:113], v[206:209], v[10:13], v[98:113]
	v_mfma_f32_32x32x16_bf16 v[82:97], v[210:213], v[10:13], v[82:97]
	v_mfma_f32_32x32x16_bf16 v[66:81], v[214:217], v[10:13], v[66:81]
	v_mfma_f32_32x32x16_bf16 v[50:65], v[218:221], v[10:13], v[50:65]
	v_mfma_f32_32x32x16_bf16 v[34:49], v[222:225], v[10:13], v[34:49]
	s_waitcnt lgkmcnt(0)
	v_mfma_f32_32x32x16_bf16 v[18:33], v[226:229], v[10:13], v[18:33]
	s_mov_b32 s6, 64
	v_add_u32_e32 v3, s6, v195
	ds_read_b128 v[14:17], v3
	ds_read_b128 v[198:201], v3 offset:32
	v_add_u32_e32 v185, s6, v194
	v_add_u32_e32 v210, s6, v193
	v_add_u32_e32 v218, s6, v192
	v_add_u32_e32 v226, s6, v191
	s_waitcnt vmcnt(12) lgkmcnt(1)
	v_mfma_f32_32x32x16_bf16 v[130:145], v[14:17], v[230:233], v[130:145]
	ds_read_b128 v[14:17], v185
	ds_read_b128 v[202:205], v185 offset:32
	s_waitcnt lgkmcnt(1)
	v_mfma_f32_32x32x16_bf16 v[114:129], v[14:17], v[230:233], v[114:129]
	ds_read_b128 v[14:17], v3 offset:17408
	ds_read_b128 v[206:209], v3 offset:17440
	s_waitcnt lgkmcnt(1)
	v_mfma_f32_32x32x16_bf16 v[98:113], v[14:17], v[230:233], v[98:113]
	ds_read_b128 v[14:17], v210
	ds_read_b128 v[210:213], v210 offset:32
	s_waitcnt lgkmcnt(1)
	v_mfma_f32_32x32x16_bf16 v[82:97], v[14:17], v[230:233], v[82:97]
	ds_read_b128 v[14:17], v3 offset:34816
	ds_read_b128 v[214:217], v3 offset:34848
	s_waitcnt lgkmcnt(1)
	v_mfma_f32_32x32x16_bf16 v[66:81], v[14:17], v[230:233], v[66:81]
	ds_read_b128 v[14:17], v218
	ds_read_b128 v[218:221], v218 offset:32
	s_waitcnt lgkmcnt(1)
	v_mfma_f32_32x32x16_bf16 v[50:65], v[14:17], v[230:233], v[50:65]
	ds_read_b128 v[14:17], v3 offset:52224
	ds_read_b128 v[222:225], v3 offset:52256
	s_waitcnt lgkmcnt(1)
	v_mfma_f32_32x32x16_bf16 v[34:49], v[14:17], v[230:233], v[34:49]
	ds_read_b128 v[14:17], v226
	ds_read_b128 v[226:229], v226 offset:32
	s_waitcnt lgkmcnt(1)
	v_mfma_f32_32x32x16_bf16 v[18:33], v[14:17], v[230:233], v[18:33]
	s_waitcnt vmcnt(11)
	v_mfma_f32_32x32x16_bf16 v[130:145], v[198:201], v[234:237], v[130:145]
	v_mfma_f32_32x32x16_bf16 v[114:129], v[202:205], v[234:237], v[114:129]
	v_mfma_f32_32x32x16_bf16 v[98:113], v[206:209], v[234:237], v[98:113]
	v_mfma_f32_32x32x16_bf16 v[82:97], v[210:213], v[234:237], v[82:97]
	v_mfma_f32_32x32x16_bf16 v[66:81], v[214:217], v[234:237], v[66:81]
	v_mfma_f32_32x32x16_bf16 v[50:65], v[218:221], v[234:237], v[50:65]
	v_mfma_f32_32x32x16_bf16 v[34:49], v[222:225], v[234:237], v[34:49]
	s_waitcnt lgkmcnt(0)
	v_mfma_f32_32x32x16_bf16 v[18:33], v[226:229], v[234:237], v[18:33]
	s_mov_b32 s6, 128
	v_add_u32_e32 v3, s6, v195
	ds_read_b128 v[14:17], v3
	ds_read_b128 v[198:201], v3 offset:32
	v_add_u32_e32 v185, s6, v194
	v_add_u32_e32 v210, s6, v193
	v_add_u32_e32 v218, s6, v192
	v_add_u32_e32 v226, s6, v191
	s_waitcnt vmcnt(14) lgkmcnt(1)
	v_mfma_f32_32x32x16_bf16 v[130:145], v[14:17], v[238:241], v[130:145]
	ds_read_b128 v[14:17], v185
	ds_read_b128 v[202:205], v185 offset:32
	s_waitcnt lgkmcnt(1)
	v_mfma_f32_32x32x16_bf16 v[114:129], v[14:17], v[238:241], v[114:129]
	ds_read_b128 v[14:17], v3 offset:17408
	ds_read_b128 v[206:209], v3 offset:17440
	s_waitcnt lgkmcnt(1)
	v_mfma_f32_32x32x16_bf16 v[98:113], v[14:17], v[238:241], v[98:113]
	ds_read_b128 v[14:17], v210
	ds_read_b128 v[210:213], v210 offset:32
	s_waitcnt lgkmcnt(1)
	v_mfma_f32_32x32x16_bf16 v[82:97], v[14:17], v[238:241], v[82:97]
	ds_read_b128 v[14:17], v3 offset:34816
	ds_read_b128 v[214:217], v3 offset:34848
	s_waitcnt lgkmcnt(1)
	v_mfma_f32_32x32x16_bf16 v[66:81], v[14:17], v[238:241], v[66:81]
	ds_read_b128 v[14:17], v218
	ds_read_b128 v[218:221], v218 offset:32
	s_waitcnt lgkmcnt(1)
	v_mfma_f32_32x32x16_bf16 v[50:65], v[14:17], v[238:241], v[50:65]
	ds_read_b128 v[14:17], v3 offset:52224
	ds_read_b128 v[222:225], v3 offset:52256
	s_waitcnt lgkmcnt(1)
	v_mfma_f32_32x32x16_bf16 v[34:49], v[14:17], v[238:241], v[34:49]
	ds_read_b128 v[14:17], v226
	ds_read_b128 v[226:229], v226 offset:32
	s_waitcnt lgkmcnt(1)
	v_mfma_f32_32x32x16_bf16 v[18:33], v[14:17], v[238:241], v[18:33]
	s_waitcnt vmcnt(10)
; #define LAS __attribute__((address_space(3)))
; #define MFMA32(a, b, c) __builtin_amdgcn_mfma_f32_32x32x16_bf16((a), (b), (c), 0, 0, 0)
; __device__ __forceinline__ void xa_item(int it, LAS unsigned char* lds, const bf16_t* XQ, const bf16_t* XK, bf16_t* PB, int tid, int wid, int lane) {
;     ...
;         if (wid < 4) {
; #pragma unroll 2
;             for (int ks = 0; ks < 8; ++ks) {
;                 const bf16x8 qv = *(const bf16x8*)(qp + c * 128 + 16 * ks);
; #pragma unroll
;                 for (int mt = 0; mt < 8; ++mt) st[mt] = MFMA32(*(const LAS bf16x8*)(KL + (32 * mt + x) * KS + 16 * ks + 8 * hi), qv, st[mt]);
;             }
;         }
;     }
;     if (wid < 4) {
;         float mx = -1e30f;
; #pragma unroll
;         for (int mt = 0; mt < 8; ++mt)
; #pragma unroll
;             for (int r = 0; r < 16; ++r) mx = fmaxf(mx, st[mt][r]);
;         mx = fmaxf(mx, __shfl_xor(mx, 32));
	v_mfma_f32_32x32x16_bf16 v[130:145], v[198:201], v[242:245], v[130:145]
	v_mfma_f32_32x32x16_bf16 v[114:129], v[202:205], v[242:245], v[114:129]
	v_mfma_f32_32x32x16_bf16 v[98:113], v[206:209], v[242:245], v[98:113]
	v_mfma_f32_32x32x16_bf16 v[82:97], v[210:213], v[242:245], v[82:97]
	v_mfma_f32_32x32x16_bf16 v[66:81], v[214:217], v[242:245], v[66:81]
	v_mfma_f32_32x32x16_bf16 v[50:65], v[218:221], v[242:245], v[50:65]
	v_mfma_f32_32x32x16_bf16 v[34:49], v[222:225], v[242:245], v[34:49]
	s_waitcnt lgkmcnt(0)
	v_mfma_f32_32x32x16_bf16 v[18:33], v[226:229], v[242:245], v[18:33]
	s_mov_b32 s6, 192
	v_add_u32_e32 v3, s6, v195
	ds_read_b128 v[14:17], v3
	ds_read_b128 v[198:201], v3 offset:32
	v_add_u32_e32 v185, s6, v194
	v_add_u32_e32 v210, s6, v193
	v_add_u32_e32 v218, s6, v192
	v_add_u32_e32 v226, s6, v191
	s_waitcnt vmcnt(9) lgkmcnt(1)
	v_mfma_f32_32x32x16_bf16 v[130:145], v[14:17], v[246:249], v[130:145]
	ds_read_b128 v[14:17], v185
	ds_read_b128 v[202:205], v185 offset:32
	s_waitcnt lgkmcnt(1)
	v_mfma_f32_32x32x16_bf16 v[114:129], v[14:17], v[246:249], v[114:129]
	ds_read_b128 v[14:17], v3 offset:17408
	ds_read_b128 v[206:209], v3 offset:17440
	s_waitcnt lgkmcnt(1)
	v_mfma_f32_32x32x16_bf16 v[98:113], v[14:17], v[246:249], v[98:113]
	ds_read_b128 v[14:17], v210
	ds_read_b128 v[210:213], v210 offset:32
	s_waitcnt lgkmcnt(1)
	v_mfma_f32_32x32x16_bf16 v[82:97], v[14:17], v[246:249], v[82:97]
	ds_read_b128 v[14:17], v3 offset:34816
	ds_read_b128 v[214:217], v3 offset:34848
	s_waitcnt lgkmcnt(1)
	v_mfma_f32_32x32x16_bf16 v[66:81], v[14:17], v[246:249], v[66:81]
	ds_read_b128 v[14:17], v218
	ds_read_b128 v[218:221], v218 offset:32
	s_waitcnt lgkmcnt(1)
	v_mfma_f32_32x32x16_bf16 v[50:65], v[14:17], v[246:249], v[50:65]
	ds_read_b128 v[14:17], v3 offset:52224
	ds_read_b128 v[222:225], v3 offset:52256
	s_waitcnt lgkmcnt(1)
	v_mfma_f32_32x32x16_bf16 v[34:49], v[14:17], v[246:249], v[34:49]
	ds_read_b128 v[14:17], v226
	ds_read_b128 v[226:229], v226 offset:32
	s_waitcnt lgkmcnt(1)
	v_mfma_f32_32x32x16_bf16 v[18:33], v[14:17], v[246:249], v[18:33]
	s_waitcnt vmcnt(8)
	v_mfma_f32_32x32x16_bf16 v[130:145], v[198:201], v[250:253], v[130:145]
	v_mfma_f32_32x32x16_bf16 v[114:129], v[202:205], v[250:253], v[114:129]
	v_mfma_f32_32x32x16_bf16 v[98:113], v[206:209], v[250:253], v[98:113]
	v_mfma_f32_32x32x16_bf16 v[82:97], v[210:213], v[250:253], v[82:97]
	v_mfma_f32_32x32x16_bf16 v[66:81], v[214:217], v[250:253], v[66:81]
	v_mfma_f32_32x32x16_bf16 v[50:65], v[218:221], v[250:253], v[50:65]
	v_mfma_f32_32x32x16_bf16 v[34:49], v[222:225], v[250:253], v[34:49]
	s_waitcnt lgkmcnt(0)
	v_mfma_f32_32x32x16_bf16 v[18:33], v[226:229], v[250:253], v[18:33]
	s_branch .LBB0_1512
.LBB0_1518:
	s_waitcnt vmcnt(0)
	s_and_b64 vcc, exec, s[2:3]
	s_cbranch_vccnz .LBB0_1510
	v_max3_f32 v3, v130, s23, v131
	v_max3_f32 v3, v3, v132, v133
	v_max3_f32 v3, v3, v134, v135
	v_max3_f32 v3, v3, v136, v137
	v_max3_f32 v3, v3, v138, v139
	v_max3_f32 v3, v3, v140, v141
	v_max3_f32 v3, v3, v142, v143
	v_max3_f32 v3, v3, v144, v145
	v_max3_f32 v3, v3, v114, v115
	v_max3_f32 v3, v3, v116, v117
	v_max3_f32 v3, v3, v118, v119
	v_max3_f32 v3, v3, v120, v121
	v_max3_f32 v3, v3, v122, v123
	v_max3_f32 v3, v3, v124, v125
	v_max3_f32 v3, v3, v126, v127
	v_max3_f32 v3, v3, v128, v129
	v_max3_f32 v3, v3, v98, v99
	v_max3_f32 v3, v3, v100, v101
	v_max3_f32 v3, v3, v102, v103
	v_max3_f32 v3, v3, v104, v105
	v_max3_f32 v3, v3, v106, v107
	v_max3_f32 v3, v3, v108, v109
	v_max3_f32 v3, v3, v110, v111
	v_max3_f32 v3, v3, v112, v113
	v_max3_f32 v3, v3, v82, v83
	v_max3_f32 v3, v3, v84, v85
	v_max3_f32 v3, v3, v86, v87
	v_max3_f32 v3, v3, v88, v89
	v_max3_f32 v3, v3, v90, v91
	v_max3_f32 v3, v3, v92, v93
	v_max3_f32 v3, v3, v94, v95
	v_max3_f32 v3, v3, v96, v97
	v_max3_f32 v3, v3, v66, v67
	v_max3_f32 v3, v3, v68, v69
	v_max3_f32 v3, v3, v70, v71
	v_max3_f32 v3, v3, v72, v73
	v_max3_f32 v3, v3, v74, v75
	v_max3_f32 v3, v3, v76, v77
	v_max3_f32 v3, v3, v78, v79
	v_max3_f32 v3, v3, v80, v81
	v_max3_f32 v3, v3, v50, v51
	v_max3_f32 v3, v3, v52, v53
	v_max3_f32 v3, v3, v54, v55
	v_max3_f32 v3, v3, v56, v57
	v_max3_f32 v3, v3, v58, v59
	v_max3_f32 v3, v3, v60, v61
	v_max3_f32 v3, v3, v62, v63
	v_max3_f32 v3, v3, v64, v65
	v_max3_f32 v3, v3, v34, v35
	v_max3_f32 v3, v3, v36, v37
	v_max3_f32 v3, v3, v38, v39
	v_max3_f32 v3, v3, v40, v41
	v_max3_f32 v3, v3, v42, v43
	v_max3_f32 v3, v3, v44, v45
	v_max3_f32 v3, v3, v46, v47
	v_max3_f32 v3, v3, v48, v49
	v_max3_f32 v3, v3, v18, v19
	v_max3_f32 v3, v3, v20, v21
	v_max3_f32 v3, v3, v22, v23
	v_max3_f32 v3, v3, v24, v25
	v_max3_f32 v3, v3, v26, v27
	v_max3_f32 v3, v3, v28, v29
	v_max3_f32 v3, v3, v30, v31
	v_and_b32_e32 v5, 64, v197
	v_max3_f32 v4, v3, v32, v33
	v_xor_b32_e32 v3, 32, v197
	v_add_u32_e32 v5, 64, v5
	v_cmp_lt_i32_e32 vcc, v3, v5
	s_lshl_b32 s2, s24, 7
	s_and_b32 s2, s2, 0xf80
	v_cndmask_b32_e32 v3, v197, v3, vcc
	v_lshlrev_b32_e32 v3, 2, v3
	ds_bpermute_b32 v5, v3, v4
	s_or_b32 s2, s12, s2
	s_waitcnt vmcnt(7)
	v_mov_b32_e32 v147, s13
	s_lshl_b32 s6, s25, 9
	v_mov_b32_e32 v185, v2
	s_waitcnt lgkmcnt(0)
; __device__ __forceinline__ void xa_item(int it, LAS unsigned char* lds, const bf16_t* XQ, const bf16_t* XK, bf16_t* PB, int tid, int wid, int lane) {
;     ...
;         float sum = 0.f;
; #pragma unroll
;         for (int mt = 0; mt < 8; ++mt)
; #pragma unroll
;             for (int r = 0; r < 16; ++r) { const float p = __builtin_amdgcn_exp2f(st[mt][r] - mx); st[mt][r] = p; sum += p; }
	v_max_f32_e32 v5, v5, v5
	v_max_f32_e32 v146, v4, v5
	v_sub_f32_e32 v16, v144, v146
	v_sub_f32_e32 v6, v132, v146
	v_exp_f32_e32 v132, v16
	v_sub_f32_e32 v16, v145, v146
	v_exp_f32_e32 v10, v6
	v_sub_f32_e32 v6, v133, v146
	v_exp_f32_e32 v133, v16
	v_sub_f32_e32 v16, v114, v146
	v_sub_f32_e32 v114, v116, v146
	v_exp_f32_e32 v11, v6
	v_sub_f32_e32 v6, v134, v146
	v_exp_f32_e32 v134, v114
	v_sub_f32_e32 v114, v117, v146
	v_sub_f32_e32 v116, v120, v146
	v_sub_f32_e32 v7, v135, v146
	v_exp_f32_e32 v135, v114
	v_sub_f32_e32 v114, v118, v146
	v_exp_f32_e32 v120, v116
	v_sub_f32_e32 v116, v121, v146
	v_sub_f32_e32 v118, v124, v146
	v_exp_f32_e32 v121, v116
	v_sub_f32_e32 v116, v122, v146
	v_exp_f32_e32 v122, v118
	v_sub_f32_e32 v118, v125, v146
	v_sub_f32_e32 v100, v100, v146
	v_sub_f32_e32 v117, v123, v146
	v_exp_f32_e32 v123, v118
	v_sub_f32_e32 v118, v126, v146
	v_exp_f32_e32 v126, v100
	v_sub_f32_e32 v100, v101, v146
	v_sub_f32_e32 v17, v115, v146
	v_sub_f32_e32 v115, v119, v146
	v_sub_f32_e32 v119, v127, v146
	v_exp_f32_e32 v127, v100
	v_sub_f32_e32 v100, v102, v146
	v_sub_f32_e32 v102, v104, v146
	v_sub_f32_e32 v124, v128, v146
	v_exp_f32_e32 v128, v102
	v_sub_f32_e32 v102, v105, v146
	v_sub_f32_e32 v104, v108, v146
	v_sub_f32_e32 v125, v129, v146
	v_exp_f32_e32 v129, v102
	v_sub_f32_e32 v102, v106, v146
	v_exp_f32_e32 v106, v104
	v_sub_f32_e32 v104, v109, v146
	v_sub_f32_e32 v84, v84, v146
	v_sub_f32_e32 v101, v103, v146
	v_sub_f32_e32 v103, v107, v146
	v_exp_f32_e32 v107, v104
	v_sub_f32_e32 v104, v110, v146
	v_exp_f32_e32 v110, v84
	v_sub_f32_e32 v84, v85, v146
	v_sub_f32_e32 v105, v111, v146
	v_exp_f32_e32 v111, v84
	v_sub_f32_e32 v84, v86, v146
	v_sub_f32_e32 v86, v88, v146
	v_sub_f32_e32 v108, v112, v146
	v_exp_f32_e32 v112, v86
	v_sub_f32_e32 v86, v89, v146
	v_sub_f32_e32 v88, v92, v146
	v_sub_f32_e32 v109, v113, v146
	v_exp_f32_e32 v113, v86
	v_sub_f32_e32 v86, v90, v146
	v_exp_f32_e32 v90, v88
	v_sub_f32_e32 v88, v93, v146
	v_sub_f32_e32 v68, v68, v146
	v_sub_f32_e32 v85, v87, v146
	v_sub_f32_e32 v87, v91, v146
	v_exp_f32_e32 v91, v88
	v_sub_f32_e32 v88, v94, v146
	v_exp_f32_e32 v94, v68
	v_sub_f32_e32 v68, v69, v146
	v_sub_f32_e32 v89, v95, v146
	v_exp_f32_e32 v95, v68
	v_sub_f32_e32 v68, v70, v146
	v_sub_f32_e32 v70, v72, v146
	v_sub_f32_e32 v92, v96, v146
	v_exp_f32_e32 v96, v70
	v_sub_f32_e32 v70, v73, v146
	v_sub_f32_e32 v72, v76, v146
	v_sub_f32_e32 v93, v97, v146
	v_exp_f32_e32 v97, v70
	v_sub_f32_e32 v70, v74, v146
	v_exp_f32_e32 v74, v72
	v_sub_f32_e32 v72, v77, v146
	v_sub_f32_e32 v52, v52, v146
	v_sub_f32_e32 v69, v71, v146
	v_sub_f32_e32 v71, v75, v146
	v_exp_f32_e32 v75, v72
	v_sub_f32_e32 v72, v78, v146
	v_exp_f32_e32 v78, v52
	v_sub_f32_e32 v52, v53, v146
	v_sub_f32_e32 v73, v79, v146
	v_exp_f32_e32 v79, v52
	v_sub_f32_e32 v52, v54, v146
	v_sub_f32_e32 v54, v56, v146
	v_sub_f32_e32 v76, v80, v146
	v_exp_f32_e32 v80, v54
	v_sub_f32_e32 v54, v57, v146
	v_sub_f32_e32 v56, v60, v146
	v_sub_f32_e32 v77, v81, v146
	v_exp_f32_e32 v81, v54
	v_sub_f32_e32 v54, v58, v146
	v_exp_f32_e32 v58, v56
	v_sub_f32_e32 v56, v61, v146
	v_sub_f32_e32 v36, v36, v146
	v_sub_f32_e32 v53, v55, v146
	v_sub_f32_e32 v55, v59, v146
	v_exp_f32_e32 v59, v56
	v_sub_f32_e32 v56, v62, v146
	v_exp_f32_e32 v62, v36
	v_sub_f32_e32 v36, v37, v146
	v_sub_f32_e32 v57, v63, v146
	v_exp_f32_e32 v63, v36
	v_sub_f32_e32 v36, v38, v146
	v_sub_f32_e32 v38, v40, v146
	v_sub_f32_e32 v60, v64, v146
	v_exp_f32_e32 v64, v38
	v_sub_f32_e32 v38, v41, v146
	v_sub_f32_e32 v40, v44, v146
	v_sub_f32_e32 v4, v130, v146
	v_sub_f32_e32 v61, v65, v146
	v_exp_f32_e32 v65, v38
	v_sub_f32_e32 v38, v42, v146
	v_exp_f32_e32 v42, v40
	v_sub_f32_e32 v40, v45, v146
	v_sub_f32_e32 v20, v20, v146
	v_exp_f32_e32 v4, v4
	v_sub_f32_e32 v5, v131, v146
	v_sub_f32_e32 v37, v39, v146
	v_sub_f32_e32 v39, v43, v146
	v_exp_f32_e32 v43, v40
	v_sub_f32_e32 v40, v46, v146
	v_exp_f32_e32 v46, v20
	v_sub_f32_e32 v20, v21, v146
	v_exp_f32_e32 v5, v5
	v_sub_f32_e32 v41, v47, v146
	v_exp_f32_e32 v47, v20
	v_sub_f32_e32 v20, v22, v146
	v_sub_f32_e32 v22, v24, v146
	v_sub_f32_e32 v44, v48, v146
	v_exp_f32_e32 v48, v22
	v_sub_f32_e32 v22, v25, v146
	v_sub_f32_e32 v24, v28, v146
	v_sub_f32_e32 v45, v49, v146
	v_exp_f32_e32 v49, v22
	v_sub_f32_e32 v22, v26, v146
	v_exp_f32_e32 v26, v24
	v_sub_f32_e32 v24, v29, v146
	v_exp_f32_e32 v6, v6
	v_sub_f32_e32 v21, v23, v146
	v_sub_f32_e32 v23, v27, v146
	v_exp_f32_e32 v27, v24
	v_sub_f32_e32 v24, v30, v146
	v_add_f32_e32 v30, 0, v4
	v_exp_f32_e32 v7, v7
	v_sub_f32_e32 v8, v136, v146
	v_add_f32_e32 v30, v5, v30
	v_exp_f32_e32 v14, v8
	v_sub_f32_e32 v8, v137, v146
	v_add_f32_e32 v30, v10, v30
	v_exp_f32_e32 v15, v8
	v_sub_f32_e32 v8, v138, v146
	v_add_f32_e32 v30, v11, v30
	v_exp_f32_e32 v8, v8
	v_sub_f32_e32 v9, v139, v146
	v_add_f32_e32 v30, v6, v30
	v_exp_f32_e32 v9, v9
	v_sub_f32_e32 v12, v140, v146
	v_add_f32_e32 v30, v7, v30
	v_exp_f32_e32 v130, v12
	v_sub_f32_e32 v12, v141, v146
	v_add_f32_e32 v30, v14, v30
	v_exp_f32_e32 v131, v12
	v_sub_f32_e32 v12, v142, v146
	v_add_f32_e32 v30, v15, v30
	v_exp_f32_e32 v12, v12
	v_sub_f32_e32 v13, v143, v146
	v_add_f32_e32 v30, v8, v30
	v_exp_f32_e32 v13, v13
	v_add_f32_e32 v30, v9, v30
	v_add_f32_e32 v30, v130, v30
	v_add_f32_e32 v30, v131, v30
	v_exp_f32_e32 v16, v16
	v_add_f32_e32 v30, v12, v30
	v_exp_f32_e32 v17, v17
	v_add_f32_e32 v30, v13, v30
	v_add_f32_e32 v30, v132, v30
	v_add_f32_e32 v30, v133, v30
	v_exp_f32_e32 v114, v114
	v_add_f32_e32 v30, v16, v30
	v_exp_f32_e32 v115, v115
	v_add_f32_e32 v30, v17, v30
	v_add_f32_e32 v30, v134, v30
	v_add_f32_e32 v30, v135, v30
	v_exp_f32_e32 v116, v116
	v_add_f32_e32 v30, v114, v30
; __device__ __forceinline__ void xa_item(int it, LAS unsigned char* lds, const bf16_t* XQ, const bf16_t* XK, bf16_t* PB, int tid, int wid, int lane) {
;     ...
;         for (int mt = 0; mt < 8; ++mt)
; #pragma unroll
;             for (int r = 0; r < 16; ++r) { const float p = __builtin_amdgcn_exp2f(st[mt][r] - mx); st[mt][r] = p; sum += p; }
;         sum += __shfl_xor(sum, 32);
;         const float inv = 1.0f / sum;
	v_exp_f32_e32 v117, v117
	v_add_f32_e32 v30, v115, v30
	v_add_f32_e32 v30, v120, v30
	v_add_f32_e32 v30, v121, v30
	v_exp_f32_e32 v118, v118
	v_add_f32_e32 v30, v116, v30
	v_exp_f32_e32 v119, v119
	v_add_f32_e32 v30, v117, v30
	v_exp_f32_e32 v124, v124
	v_add_f32_e32 v30, v122, v30
	v_exp_f32_e32 v125, v125
	v_sub_f32_e32 v98, v98, v146
	v_add_f32_e32 v30, v123, v30
	v_exp_f32_e32 v98, v98
	v_sub_f32_e32 v99, v99, v146
	v_add_f32_e32 v30, v118, v30
	v_exp_f32_e32 v99, v99
	v_add_f32_e32 v30, v119, v30
	v_add_f32_e32 v30, v124, v30
	v_add_f32_e32 v30, v125, v30
	v_exp_f32_e32 v100, v100
	v_add_f32_e32 v30, v98, v30
	v_exp_f32_e32 v101, v101
	v_add_f32_e32 v30, v99, v30
	v_add_f32_e32 v30, v126, v30
	v_add_f32_e32 v30, v127, v30
	v_exp_f32_e32 v102, v102
	v_add_f32_e32 v30, v100, v30
	v_exp_f32_e32 v103, v103
	v_add_f32_e32 v30, v101, v30
	v_add_f32_e32 v30, v128, v30
	v_add_f32_e32 v30, v129, v30
	v_exp_f32_e32 v104, v104
	v_add_f32_e32 v30, v102, v30
	v_exp_f32_e32 v105, v105
	v_add_f32_e32 v30, v103, v30
	v_exp_f32_e32 v108, v108
	v_add_f32_e32 v30, v106, v30
	v_exp_f32_e32 v109, v109
	v_sub_f32_e32 v82, v82, v146
	v_add_f32_e32 v30, v107, v30
	v_exp_f32_e32 v82, v82
	v_sub_f32_e32 v83, v83, v146
	v_add_f32_e32 v30, v104, v30
	v_exp_f32_e32 v83, v83
	v_add_f32_e32 v30, v105, v30
	v_add_f32_e32 v30, v108, v30
	v_add_f32_e32 v30, v109, v30
	v_exp_f32_e32 v84, v84
	v_add_f32_e32 v30, v82, v30
	v_exp_f32_e32 v85, v85
	v_add_f32_e32 v30, v83, v30
	v_add_f32_e32 v30, v110, v30
	v_add_f32_e32 v30, v111, v30
	v_exp_f32_e32 v86, v86
	v_add_f32_e32 v30, v84, v30
	v_exp_f32_e32 v87, v87
	v_add_f32_e32 v30, v85, v30
	v_add_f32_e32 v30, v112, v30
	v_add_f32_e32 v30, v113, v30
	v_exp_f32_e32 v88, v88
	v_add_f32_e32 v30, v86, v30
	v_exp_f32_e32 v89, v89
	v_add_f32_e32 v30, v87, v30
	v_exp_f32_e32 v92, v92
	v_add_f32_e32 v30, v90, v30
	v_exp_f32_e32 v93, v93
	v_sub_f32_e32 v66, v66, v146
	v_add_f32_e32 v30, v91, v30
	v_exp_f32_e32 v66, v66
	v_sub_f32_e32 v67, v67, v146
	v_add_f32_e32 v30, v88, v30
	v_exp_f32_e32 v67, v67
	v_add_f32_e32 v30, v89, v30
	v_add_f32_e32 v30, v92, v30
	v_add_f32_e32 v30, v93, v30
	v_exp_f32_e32 v68, v68
	v_add_f32_e32 v30, v66, v30
	v_exp_f32_e32 v69, v69
	v_add_f32_e32 v30, v67, v30
	v_add_f32_e32 v30, v94, v30
	v_add_f32_e32 v30, v95, v30
	v_exp_f32_e32 v70, v70
	v_add_f32_e32 v30, v68, v30
	v_exp_f32_e32 v71, v71
	v_add_f32_e32 v30, v69, v30
	v_add_f32_e32 v30, v96, v30
	v_add_f32_e32 v30, v97, v30
	v_exp_f32_e32 v72, v72
	v_add_f32_e32 v30, v70, v30
	v_exp_f32_e32 v73, v73
	v_add_f32_e32 v30, v71, v30
	v_exp_f32_e32 v76, v76
	v_add_f32_e32 v30, v74, v30
	v_exp_f32_e32 v77, v77
	v_sub_f32_e32 v50, v50, v146
	v_add_f32_e32 v30, v75, v30
	v_exp_f32_e32 v50, v50
	v_sub_f32_e32 v51, v51, v146
	v_add_f32_e32 v30, v72, v30
	v_exp_f32_e32 v51, v51
	v_add_f32_e32 v30, v73, v30
	v_add_f32_e32 v30, v76, v30
	v_add_f32_e32 v30, v77, v30
	v_exp_f32_e32 v52, v52
	v_add_f32_e32 v30, v50, v30
	v_exp_f32_e32 v53, v53
	v_add_f32_e32 v30, v51, v30
	v_add_f32_e32 v30, v78, v30
	v_add_f32_e32 v30, v79, v30
	v_exp_f32_e32 v54, v54
	v_add_f32_e32 v30, v52, v30
	v_exp_f32_e32 v55, v55
	v_add_f32_e32 v30, v53, v30
	v_add_f32_e32 v30, v80, v30
	v_add_f32_e32 v30, v81, v30
	v_exp_f32_e32 v56, v56
	v_add_f32_e32 v30, v54, v30
	v_exp_f32_e32 v57, v57
	v_add_f32_e32 v30, v55, v30
	v_exp_f32_e32 v60, v60
	v_add_f32_e32 v30, v58, v30
	v_exp_f32_e32 v61, v61
	v_sub_f32_e32 v34, v34, v146
	v_add_f32_e32 v30, v59, v30
	v_exp_f32_e32 v34, v34
	v_sub_f32_e32 v35, v35, v146
	v_add_f32_e32 v30, v56, v30
	v_exp_f32_e32 v35, v35
	v_add_f32_e32 v30, v57, v30
	v_add_f32_e32 v30, v60, v30
	v_add_f32_e32 v30, v61, v30
	v_exp_f32_e32 v36, v36
	v_add_f32_e32 v30, v34, v30
	v_exp_f32_e32 v37, v37
	v_add_f32_e32 v30, v35, v30
	v_add_f32_e32 v30, v62, v30
	v_add_f32_e32 v30, v63, v30
	v_exp_f32_e32 v38, v38
	v_add_f32_e32 v30, v36, v30
	v_exp_f32_e32 v39, v39
	v_add_f32_e32 v30, v37, v30
	v_add_f32_e32 v30, v64, v30
	v_add_f32_e32 v30, v65, v30
	v_exp_f32_e32 v40, v40
	v_add_f32_e32 v30, v38, v30
	v_exp_f32_e32 v41, v41
	v_add_f32_e32 v30, v39, v30
	v_exp_f32_e32 v44, v44
	v_add_f32_e32 v30, v42, v30
	v_exp_f32_e32 v45, v45
	v_sub_f32_e32 v18, v18, v146
	v_add_f32_e32 v30, v43, v30
	v_exp_f32_e32 v18, v18
	v_sub_f32_e32 v19, v19, v146
	v_add_f32_e32 v30, v40, v30
	v_exp_f32_e32 v19, v19
	v_add_f32_e32 v30, v41, v30
	v_add_f32_e32 v30, v44, v30
	v_add_f32_e32 v30, v45, v30
	v_exp_f32_e32 v20, v20
	v_add_f32_e32 v30, v18, v30
	v_exp_f32_e32 v21, v21
	v_add_f32_e32 v30, v19, v30
	v_add_f32_e32 v30, v46, v30
	v_add_f32_e32 v30, v47, v30
	v_exp_f32_e32 v22, v22
	v_add_f32_e32 v30, v20, v30
	v_exp_f32_e32 v23, v23
	v_add_f32_e32 v30, v21, v30
	v_add_f32_e32 v30, v48, v30
	v_add_f32_e32 v30, v49, v30
	v_exp_f32_e32 v24, v24
	v_sub_f32_e32 v25, v31, v146
	v_add_f32_e32 v30, v22, v30
	v_exp_f32_e32 v25, v25
	v_sub_f32_e32 v28, v32, v146
	v_add_f32_e32 v30, v23, v30
	v_exp_f32_e32 v28, v28
	v_sub_f32_e32 v29, v33, v146
	v_add_f32_e32 v30, v26, v30
	v_exp_f32_e32 v29, v29
	v_add_f32_e32 v30, v27, v30
	v_add_f32_e32 v30, v24, v30
	v_add_f32_e32 v30, v25, v30
	v_add_f32_e32 v30, v28, v30
	v_add_f32_e32 v32, v29, v30
	ds_bpermute_b32 v3, v3, v32
	v_or_b32_e32 v146, s2, v178
	v_readlane_b32 s2, v254, 52
	v_lshlrev_b64 v[30:31], 11, v[146:147]
	v_readlane_b32 s3, v254, 53
	s_waitcnt lgkmcnt(0)
; __device__ __forceinline__ unsigned cvtpk(float lo, float hi) { f32x2_t v = {lo, hi}; bf16x2_t b = __builtin_convertvector(v, bf16x2_t); return __builtin_bit_cast(unsigned, b); }
; __device__ __forceinline__ void xa_item(int it, LAS unsigned char* lds, const bf16_t* XQ, const bf16_t* XK, bf16_t* PB, int tid, int wid, int lane) {
;     ...
;         sum += __shfl_xor(sum, 32);
;         const float inv = 1.0f / sum;
;         bf16_t* op = PB + qrow * 1024 + head * 256 + 4 * hi;
; #pragma unroll
;         for (int mt = 0; mt < 8; ++mt)
; #pragma unroll
;             for (int g = 0; g < 4; ++g) { u32x2 w; w.x = cvtpk(st[mt][4 * g] * inv, st[mt][4 * g + 1] * inv); w.y = cvtpk(st[mt][4 * g + 2] * inv, st[mt][4 * g + 3] * inv); *(u32x2*)(op + 32 * mt + 8 * g) = w; }
	v_add_f32_e32 v3, v32, v3
	v_lshl_add_u64 v[30:31], s[2:3], 0, v[30:31]
	v_div_scale_f32 v32, s[2:3], v3, v3, 1.0
	v_rcp_f32_e32 v33, v32
	v_lshl_add_u64 v[30:31], v[30:31], 0, s[6:7]
	v_lshl_add_u64 v[30:31], v[30:31], 0, v[184:185]
	v_fma_f32 v136, -v32, v33, 1.0
	v_fmac_f32_e32 v33, v136, v33
	v_div_scale_f32 v136, vcc, 1.0, v3, 1.0
	v_mul_f32_e32 v137, v136, v33
	v_fma_f32 v138, -v32, v137, v136
	v_fmac_f32_e32 v137, v138, v33
	v_fma_f32 v32, -v32, v137, v136
	v_div_fmas_f32 v32, v32, v33, v137
	v_div_fixup_f32 v32, v32, v3, 1.0
	v_pk_mul_f32 v[4:5], v[4:5], v[32:33] op_sel_hi:[1,0]
	v_pk_mul_f32 v[10:11], v[10:11], v[32:33] op_sel_hi:[1,0]
	v_cvt_pk_bf16_f32 v4, v4, v5
	v_cvt_pk_bf16_f32 v5, v10, v11
	global_store_dwordx2 v[30:31], v[4:5], off
	v_pk_mul_f32 v[4:5], v[6:7], v[32:33] op_sel_hi:[1,0]
	v_pk_mul_f32 v[6:7], v[14:15], v[32:33] op_sel_hi:[1,0]
	v_cvt_pk_bf16_f32 v4, v4, v5
	v_cvt_pk_bf16_f32 v5, v6, v7
	global_store_dwordx2 v[30:31], v[4:5], off offset:16
	v_pk_mul_f32 v[4:5], v[8:9], v[32:33] op_sel_hi:[1,0]
	v_pk_mul_f32 v[6:7], v[130:131], v[32:33] op_sel_hi:[1,0]
	v_cvt_pk_bf16_f32 v4, v4, v5
	v_cvt_pk_bf16_f32 v5, v6, v7
	global_store_dwordx2 v[30:31], v[4:5], off offset:32
	v_pk_mul_f32 v[4:5], v[12:13], v[32:33] op_sel_hi:[1,0]
	v_pk_mul_f32 v[6:7], v[132:133], v[32:33] op_sel_hi:[1,0]
	v_cvt_pk_bf16_f32 v4, v4, v5
	v_cvt_pk_bf16_f32 v5, v6, v7
	global_store_dwordx2 v[30:31], v[4:5], off offset:48
	v_pk_mul_f32 v[4:5], v[16:17], v[32:33] op_sel_hi:[1,0]
	v_pk_mul_f32 v[6:7], v[134:135], v[32:33] op_sel_hi:[1,0]
	v_cvt_pk_bf16_f32 v4, v4, v5
	v_cvt_pk_bf16_f32 v5, v6, v7
	global_store_dwordx2 v[30:31], v[4:5], off offset:64
	v_pk_mul_f32 v[4:5], v[114:115], v[32:33] op_sel_hi:[1,0]
	v_pk_mul_f32 v[6:7], v[120:121], v[32:33] op_sel_hi:[1,0]
	v_cvt_pk_bf16_f32 v4, v4, v5
	v_cvt_pk_bf16_f32 v5, v6, v7
	global_store_dwordx2 v[30:31], v[4:5], off offset:80
	v_pk_mul_f32 v[4:5], v[116:117], v[32:33] op_sel_hi:[1,0]
	v_pk_mul_f32 v[6:7], v[122:123], v[32:33] op_sel_hi:[1,0]
	v_cvt_pk_bf16_f32 v4, v4, v5
	v_cvt_pk_bf16_f32 v5, v6, v7
	global_store_dwordx2 v[30:31], v[4:5], off offset:96
	v_pk_mul_f32 v[4:5], v[118:119], v[32:33] op_sel_hi:[1,0]
	v_pk_mul_f32 v[6:7], v[124:125], v[32:33] op_sel_hi:[1,0]
	v_cvt_pk_bf16_f32 v4, v4, v5
	v_cvt_pk_bf16_f32 v5, v6, v7
	global_store_dwordx2 v[30:31], v[4:5], off offset:112
	v_pk_mul_f32 v[4:5], v[98:99], v[32:33] op_sel_hi:[1,0]
	v_pk_mul_f32 v[6:7], v[126:127], v[32:33] op_sel_hi:[1,0]
	v_cvt_pk_bf16_f32 v4, v4, v5
	v_cvt_pk_bf16_f32 v5, v6, v7
	global_store_dwordx2 v[30:31], v[4:5], off offset:128
	v_pk_mul_f32 v[4:5], v[100:101], v[32:33] op_sel_hi:[1,0]
	v_pk_mul_f32 v[6:7], v[128:129], v[32:33] op_sel_hi:[1,0]
	v_cvt_pk_bf16_f32 v4, v4, v5
	v_cvt_pk_bf16_f32 v5, v6, v7
	global_store_dwordx2 v[30:31], v[4:5], off offset:144
	v_pk_mul_f32 v[4:5], v[102:103], v[32:33] op_sel_hi:[1,0]
	v_pk_mul_f32 v[6:7], v[106:107], v[32:33] op_sel_hi:[1,0]
	v_cvt_pk_bf16_f32 v4, v4, v5
	v_cvt_pk_bf16_f32 v5, v6, v7
	global_store_dwordx2 v[30:31], v[4:5], off offset:160
	v_pk_mul_f32 v[4:5], v[104:105], v[32:33] op_sel_hi:[1,0]
	v_pk_mul_f32 v[6:7], v[108:109], v[32:33] op_sel_hi:[1,0]
	v_cvt_pk_bf16_f32 v4, v4, v5
	v_cvt_pk_bf16_f32 v5, v6, v7
	global_store_dwordx2 v[30:31], v[4:5], off offset:176
	v_pk_mul_f32 v[4:5], v[82:83], v[32:33] op_sel_hi:[1,0]
	v_pk_mul_f32 v[6:7], v[110:111], v[32:33] op_sel_hi:[1,0]
	v_cvt_pk_bf16_f32 v4, v4, v5
	v_cvt_pk_bf16_f32 v5, v6, v7
	global_store_dwordx2 v[30:31], v[4:5], off offset:192
	v_pk_mul_f32 v[4:5], v[84:85], v[32:33] op_sel_hi:[1,0]
	v_pk_mul_f32 v[6:7], v[112:113], v[32:33] op_sel_hi:[1,0]
	v_cvt_pk_bf16_f32 v4, v4, v5
	v_cvt_pk_bf16_f32 v5, v6, v7
	global_store_dwordx2 v[30:31], v[4:5], off offset:208
	v_pk_mul_f32 v[4:5], v[86:87], v[32:33] op_sel_hi:[1,0]
	v_pk_mul_f32 v[6:7], v[90:91], v[32:33] op_sel_hi:[1,0]
	v_cvt_pk_bf16_f32 v4, v4, v5
	v_cvt_pk_bf16_f32 v5, v6, v7
; __device__ __forceinline__ unsigned cvtpk(float lo, float hi) { f32x2_t v = {lo, hi}; bf16x2_t b = __builtin_convertvector(v, bf16x2_t); return __builtin_bit_cast(unsigned, b); }
; __device__ __forceinline__ void xa_item(int it, LAS unsigned char* lds, const bf16_t* XQ, const bf16_t* XK, bf16_t* PB, int tid, int wid, int lane) {
;     ...
; #pragma unroll
;         for (int mt = 0; mt < 8; ++mt)
; #pragma unroll
;             for (int g = 0; g < 4; ++g) { u32x2 w; w.x = cvtpk(st[mt][4 * g] * inv, st[mt][4 * g + 1] * inv); w.y = cvtpk(st[mt][4 * g + 2] * inv, st[mt][4 * g + 3] * inv); *(u32x2*)(op + 32 * mt + 8 * g) = w; }
	global_store_dwordx2 v[30:31], v[4:5], off offset:224
	v_pk_mul_f32 v[4:5], v[88:89], v[32:33] op_sel_hi:[1,0]
	v_pk_mul_f32 v[6:7], v[92:93], v[32:33] op_sel_hi:[1,0]
	v_cvt_pk_bf16_f32 v4, v4, v5
	v_cvt_pk_bf16_f32 v5, v6, v7
	global_store_dwordx2 v[30:31], v[4:5], off offset:240
	v_pk_mul_f32 v[4:5], v[66:67], v[32:33] op_sel_hi:[1,0]
	v_pk_mul_f32 v[6:7], v[94:95], v[32:33] op_sel_hi:[1,0]
	v_cvt_pk_bf16_f32 v4, v4, v5
	v_cvt_pk_bf16_f32 v5, v6, v7
	global_store_dwordx2 v[30:31], v[4:5], off offset:256
	v_pk_mul_f32 v[4:5], v[68:69], v[32:33] op_sel_hi:[1,0]
	v_pk_mul_f32 v[6:7], v[96:97], v[32:33] op_sel_hi:[1,0]
	v_cvt_pk_bf16_f32 v4, v4, v5
	v_cvt_pk_bf16_f32 v5, v6, v7
	global_store_dwordx2 v[30:31], v[4:5], off offset:272
	v_pk_mul_f32 v[4:5], v[70:71], v[32:33] op_sel_hi:[1,0]
	v_pk_mul_f32 v[6:7], v[74:75], v[32:33] op_sel_hi:[1,0]
	v_cvt_pk_bf16_f32 v4, v4, v5
	v_cvt_pk_bf16_f32 v5, v6, v7
	global_store_dwordx2 v[30:31], v[4:5], off offset:288
	v_pk_mul_f32 v[4:5], v[72:73], v[32:33] op_sel_hi:[1,0]
	v_pk_mul_f32 v[6:7], v[76:77], v[32:33] op_sel_hi:[1,0]
	v_cvt_pk_bf16_f32 v4, v4, v5
	v_cvt_pk_bf16_f32 v5, v6, v7
	global_store_dwordx2 v[30:31], v[4:5], off offset:304
	v_pk_mul_f32 v[4:5], v[50:51], v[32:33] op_sel_hi:[1,0]
	v_pk_mul_f32 v[6:7], v[78:79], v[32:33] op_sel_hi:[1,0]
	v_cvt_pk_bf16_f32 v4, v4, v5
	v_cvt_pk_bf16_f32 v5, v6, v7
	global_store_dwordx2 v[30:31], v[4:5], off offset:320
	v_pk_mul_f32 v[4:5], v[52:53], v[32:33] op_sel_hi:[1,0]
	v_pk_mul_f32 v[6:7], v[80:81], v[32:33] op_sel_hi:[1,0]
	v_cvt_pk_bf16_f32 v4, v4, v5
	v_cvt_pk_bf16_f32 v5, v6, v7
	global_store_dwordx2 v[30:31], v[4:5], off offset:336
	v_pk_mul_f32 v[4:5], v[54:55], v[32:33] op_sel_hi:[1,0]
	v_pk_mul_f32 v[6:7], v[58:59], v[32:33] op_sel_hi:[1,0]
	v_cvt_pk_bf16_f32 v4, v4, v5
	v_cvt_pk_bf16_f32 v5, v6, v7
	global_store_dwordx2 v[30:31], v[4:5], off offset:352
	v_pk_mul_f32 v[4:5], v[56:57], v[32:33] op_sel_hi:[1,0]
	v_pk_mul_f32 v[6:7], v[60:61], v[32:33] op_sel_hi:[1,0]
	v_cvt_pk_bf16_f32 v4, v4, v5
	v_cvt_pk_bf16_f32 v5, v6, v7
	global_store_dwordx2 v[30:31], v[4:5], off offset:368
	v_pk_mul_f32 v[4:5], v[34:35], v[32:33] op_sel_hi:[1,0]
	v_pk_mul_f32 v[6:7], v[62:63], v[32:33] op_sel_hi:[1,0]
	v_cvt_pk_bf16_f32 v4, v4, v5
	v_cvt_pk_bf16_f32 v5, v6, v7
	global_store_dwordx2 v[30:31], v[4:5], off offset:384
	v_pk_mul_f32 v[4:5], v[36:37], v[32:33] op_sel_hi:[1,0]
	v_pk_mul_f32 v[6:7], v[64:65], v[32:33] op_sel_hi:[1,0]
	v_cvt_pk_bf16_f32 v4, v4, v5
	v_cvt_pk_bf16_f32 v5, v6, v7
	global_store_dwordx2 v[30:31], v[4:5], off offset:400
	v_pk_mul_f32 v[4:5], v[38:39], v[32:33] op_sel_hi:[1,0]
	v_pk_mul_f32 v[6:7], v[42:43], v[32:33] op_sel_hi:[1,0]
	v_cvt_pk_bf16_f32 v4, v4, v5
	v_cvt_pk_bf16_f32 v5, v6, v7
	global_store_dwordx2 v[30:31], v[4:5], off offset:416
	v_pk_mul_f32 v[4:5], v[40:41], v[32:33] op_sel_hi:[1,0]
	v_pk_mul_f32 v[6:7], v[44:45], v[32:33] op_sel_hi:[1,0]
	v_cvt_pk_bf16_f32 v4, v4, v5
	v_cvt_pk_bf16_f32 v5, v6, v7
	global_store_dwordx2 v[30:31], v[4:5], off offset:432
	v_pk_mul_f32 v[4:5], v[18:19], v[32:33] op_sel_hi:[1,0]
	v_pk_mul_f32 v[6:7], v[46:47], v[32:33] op_sel_hi:[1,0]
	v_cvt_pk_bf16_f32 v4, v4, v5
	v_cvt_pk_bf16_f32 v5, v6, v7
	global_store_dwordx2 v[30:31], v[4:5], off offset:448
	v_pk_mul_f32 v[4:5], v[20:21], v[32:33] op_sel_hi:[1,0]
	v_pk_mul_f32 v[6:7], v[48:49], v[32:33] op_sel_hi:[1,0]
	v_cvt_pk_bf16_f32 v4, v4, v5
	v_cvt_pk_bf16_f32 v5, v6, v7
	global_store_dwordx2 v[30:31], v[4:5], off offset:464
	v_pk_mul_f32 v[4:5], v[22:23], v[32:33] op_sel_hi:[1,0]
	v_pk_mul_f32 v[6:7], v[26:27], v[32:33] op_sel_hi:[1,0]
	v_cvt_pk_bf16_f32 v4, v4, v5
	v_cvt_pk_bf16_f32 v5, v6, v7
	global_store_dwordx2 v[30:31], v[4:5], off offset:480
	v_pk_mul_f32 v[4:5], v[24:25], v[32:33] op_sel_hi:[1,0]
	v_pk_mul_f32 v[6:7], v[28:29], v[32:33] op_sel_hi:[1,0]
	v_cvt_pk_bf16_f32 v4, v4, v5
	v_cvt_pk_bf16_f32 v5, v6, v7
	global_store_dwordx2 v[30:31], v[4:5], off offset:496
	s_branch .LBB0_1510
